# GroupNorm gain/bias loads overlap the first row's loads (no drain before the row loop) + LoRA loads at phase-0 start
# baseline (speedup 1.0000x reference)
.LBB0_628:
	v_lshl_add_u64 v[34:35], v[8:9], 0, v[6:7]
	v_add_co_u32_e32 v60, vcc, 0x14a08000, v34
	v_lshl_add_u64 v[46:47], s[68:69], 0, v[26:27]
	s_nop 0
	v_addc_co_u32_e32 v61, vcc, 0, v35, vcc
	v_add_co_u32_e32 v34, vcc, 0xb900000, v34
	v_lshl_add_u64 v[48:49], v[10:11], 0, v[6:7]
	v_lshl_add_u64 v[50:51], s[68:69], 0, v[28:29]
	v_addc_co_u32_e32 v35, vcc, 0, v35, vcc
	v_lshl_add_u64 v[54:55], s[68:69], 0, v[24:25]
	v_lshl_add_u64 v[58:59], s[68:69], 0, v[20:21]
	global_load_dword v72, v[22:23], off offset:-32
	global_load_dword v73, v[22:23], off offset:-16
	global_load_dword v74, v[22:23], off
	global_load_dword v75, v[22:23], off offset:16
	global_load_dwordx2 v[62:63], v[46:47], off
	global_load_dwordx2 v[64:65], v[50:51], off
	global_load_dwordx2 v[66:67], v[54:55], off
	global_load_dwordx2 v[32:33], v[58:59], off
	v_add_co_u32_e32 v50, vcc, s3, v48
	global_load_dwordx2 v[46:47], v[60:61], off
	s_nop 0
	v_addc_co_u32_e32 v51, vcc, 0, v49, vcc
	global_load_dwordx2 v[54:55], v[34:35], off
	v_add_co_u32_e32 v34, vcc, s11, v48
	global_load_dwordx2 v[50:51], v[50:51], off
	v_lshl_add_u64 v[52:53], v[16:17], 0, v[6:7]
	v_addc_co_u32_e32 v35, vcc, 0, v49, vcc
	v_add_co_u32_e32 v48, vcc, s3, v52
	global_load_dwordx2 v[58:59], v[34:35], off
	s_nop 0
	v_addc_co_u32_e32 v49, vcc, 0, v53, vcc
	v_add_co_u32_e32 v34, vcc, s11, v52
	v_lshl_add_u64 v[56:57], v[18:19], 0, v[6:7]
	s_nop 0
	v_addc_co_u32_e32 v35, vcc, 0, v53, vcc
	v_add_co_u32_e32 v52, vcc, s3, v56
	global_load_dwordx2 v[48:49], v[48:49], off
	s_nop 0
	global_load_dwordx2 v[60:61], v[34:35], off
	v_addc_co_u32_e32 v53, vcc, 0, v57, vcc
	v_add_co_u32_e32 v34, vcc, s11, v56
	v_mov_b64_e32 v[36:37], s[22:23]
	s_nop 0
	v_addc_co_u32_e32 v35, vcc, 0, v57, vcc
	v_lshl_add_u64 v[30:31], v[14:15], 0, v[12:13]
	global_load_dwordx2 v[52:53], v[52:53], off
	s_nop 0
	global_load_dwordx2 v[34:35], v[34:35], off
	v_add_u32_e32 v1, s10, v1
	v_lshl_add_u64 v[8:9], v[8:9], 0, s[12:13]
	v_lshl_add_u64 v[10:11], v[10:11], 0, s[12:13]
	v_lshl_add_u64 v[12:13], v[12:13], 0, s[12:13]
	v_lshl_add_u64 v[16:17], v[16:17], 0, s[12:13]
	v_lshl_add_u64 v[18:19], v[18:19], 0, s[12:13]
	v_lshl_add_u64 v[20:21], v[20:21], 0, s[14:15]
	v_lshl_add_u64 v[22:23], v[22:23], 0, s[16:17]
	v_lshl_add_u64 v[24:25], v[24:25], 0, s[14:15]
	v_lshl_add_u64 v[26:27], v[26:27], 0, s[14:15]
	v_lshl_add_u64 v[28:29], v[28:29], 0, s[14:15]
	s_waitcnt vmcnt(11)
	v_lshlrev_b32_e32 v76, 16, v62
	v_and_b32_e32 v77, 0xffff0000, v62
	v_lshlrev_b32_e32 v78, 16, v63
	v_and_b32_e32 v79, 0xffff0000, v63
	s_waitcnt vmcnt(7)
	v_lshlrev_b32_e32 v57, 16, v47
	v_lshlrev_b32_e32 v56, 16, v46
	v_and_b32_e32 v47, 0xffff0000, v47
	v_and_b32_e32 v46, 0xffff0000, v46
	v_pk_add_f32 v[62:63], v[56:57], v[46:47]
	s_waitcnt vmcnt(6)
	v_lshlrev_b32_e32 v80, 16, v54
	v_and_b32_e32 v81, 0xffff0000, v54
	v_lshlrev_b32_e32 v82, 16, v55
	v_and_b32_e32 v83, 0xffff0000, v55
	v_add_f32_e32 v62, v62, v63
	s_waitcnt vmcnt(5)
	v_lshlrev_b32_e32 v55, 16, v51
	v_lshlrev_b32_e32 v54, 16, v50
	v_and_b32_e32 v51, 0xffff0000, v51
	v_and_b32_e32 v50, 0xffff0000, v50
	v_add_f32_dpp v68, v62, v62 quad_perm:[1,0,3,2] row_mask:0xf bank_mask:0xf bound_ctrl:1
	v_pk_add_f32 v[62:63], v[54:55], v[50:51]
	s_nop 0
	v_add_f32_dpp v68, v68, v68 quad_perm:[2,3,0,1] row_mask:0xf bank_mask:0xf bound_ctrl:1
	v_add_f32_e32 v62, v62, v63
	s_nop 0
	v_add_f32_dpp v63, v68, v68 row_half_mirror row_mask:0xf bank_mask:0xf bound_ctrl:1
	v_add_f32_dpp v62, v62, v62 quad_perm:[1,0,3,2] row_mask:0xf bank_mask:0xf bound_ctrl:1
	s_nop 0
	v_add_f32_dpp v63, v63, v63 row_mirror row_mask:0xf bank_mask:0xf bound_ctrl:1
	v_add_f32_dpp v68, v62, v62 quad_perm:[2,3,0,1] row_mask:0xf bank_mask:0xf bound_ctrl:1
	v_mul_f32_e32 v62, 0x3c800000, v63
	s_nop 0
	v_add_f32_dpp v63, v68, v68 row_half_mirror row_mask:0xf bank_mask:0xf bound_ctrl:1
	v_pk_add_f32 v[46:47], v[46:47], v[62:63] op_sel_hi:[1,0] neg_lo:[0,1] neg_hi:[0,1]
	v_pk_add_f32 v[56:57], v[56:57], v[62:63] op_sel_hi:[1,0] neg_lo:[0,1] neg_hi:[0,1]
	v_add_f32_dpp v68, v63, v63 row_mirror row_mask:0xf bank_mask:0xf bound_ctrl:1
	v_mul_f32_e32 v68, 0x3c800000, v68
	v_pk_add_f32 v[50:51], v[50:51], v[68:69] op_sel_hi:[1,0] neg_lo:[0,1] neg_hi:[0,1]
	v_pk_mul_f32 v[62:63], v[46:47], v[46:47]
	v_pk_add_f32 v[54:55], v[54:55], v[68:69] op_sel_hi:[1,0] neg_lo:[0,1] neg_hi:[0,1]
	v_pk_mul_f32 v[68:69], v[50:51], v[50:51]
	v_pk_fma_f32 v[62:63], v[56:57], v[56:57], v[62:63]
	v_pk_fma_f32 v[68:69], v[54:55], v[54:55], v[68:69]
	v_mov_b32_e32 v71, v62
	v_mov_b32_e32 v70, v68
	v_mov_b32_e32 v62, v69
	v_pk_add_f32 v[62:63], v[70:71], v[62:63]
	s_waitcnt vmcnt(4)
	v_mov_b32_e32 v38, v140
	v_mov_b32_e32 v39, v141
	v_mov_b32_e32 v40, v142
	v_mov_b32_e32 v41, v143
	v_mov_b32_e32 v42, v144
	v_mov_b32_e32 v43, v145
	v_mov_b32_e32 v44, v146
	v_mov_b32_e32 v45, v147
	v_lshlrev_b32_e32 v71, 16, v58
	v_and_b32_e32 v58, 0xffff0000, v58
	v_mov_b32_dpp v69, v63 quad_perm:[1,0,3,2] row_mask:0xf bank_mask:0xf bound_ctrl:1
	v_mov_b32_dpp v68, v62 quad_perm:[1,0,3,2] row_mask:0xf bank_mask:0xf bound_ctrl:1
	v_pk_add_f32 v[62:63], v[62:63], v[68:69]
	v_lshlrev_b32_e32 v70, 16, v67
	v_and_b32_e32 v67, 0xffff0000, v67
	v_mov_b32_dpp v69, v63 quad_perm:[2,3,0,1] row_mask:0xf bank_mask:0xf bound_ctrl:1
	v_mov_b32_dpp v68, v62 quad_perm:[2,3,0,1] row_mask:0xf bank_mask:0xf bound_ctrl:1
	v_pk_add_f32 v[62:63], v[62:63], v[68:69]
	s_nop 1
	v_mov_b32_dpp v69, v63 row_half_mirror row_mask:0xf bank_mask:0xf bound_ctrl:1
	v_mov_b32_dpp v68, v62 row_half_mirror row_mask:0xf bank_mask:0xf bound_ctrl:1
	v_pk_add_f32 v[62:63], v[62:63], v[68:69]
	s_nop 1
	v_mov_b32_dpp v69, v63 row_mirror row_mask:0xf bank_mask:0xf bound_ctrl:1
	v_mov_b32_dpp v68, v62 row_mirror row_mask:0xf bank_mask:0xf bound_ctrl:1
	v_pk_add_f32 v[62:63], v[62:63], v[68:69]
	v_lshlrev_b32_e32 v69, 16, v66
	v_pk_fma_f32 v[62:63], v[62:63], s[20:21], v[36:37] op_sel_hi:[1,0,0]
	v_and_b32_e32 v66, 0xffff0000, v66
	v_mul_f32_e32 v68, 0x4b800000, v63
	v_cmp_gt_f32_e32 vcc, s21, v63
	s_nop 1
	v_cndmask_b32_e32 v63, v63, v68, vcc
	v_rsq_f32_e32 v63, v63
	s_nop 0
	v_mul_f32_e32 v68, 0x45800000, v63
	v_cndmask_b32_e32 v63, v63, v68, vcc
	v_mul_f32_e32 v56, v56, v63
	v_mul_f32_e32 v46, v46, v63
	v_mul_f32_e32 v57, v57, v63
	v_mul_f32_e32 v47, v47, v63
	v_fma_f32 v38, v38, v56, v42
	v_fma_f32 v39, v39, v46, v43
	v_fma_f32 v40, v40, v57, v44
	v_fmac_f32_e32 v45, v41, v47
	v_fmac_f32_e32 v38, v72, v76
	v_fmac_f32_e32 v39, v72, v77
	v_fmac_f32_e32 v40, v72, v78
	v_fmac_f32_e32 v45, v72, v79
	v_mul_f32_e32 v38, v38, v80
	v_mul_f32_e32 v39, v39, v81
	v_mul_f32_e32 v40, v40, v82
	v_mul_f32_e32 v41, v45, v83
	v_cvt_pk_bf16_f32 v38, v38, v39
	v_cvt_pk_bf16_f32 v39, v40, v41
	global_store_dwordx2 v[30:31], v[38:39], off offset:-1024
	s_nop 1
	v_mov_b32_e32 v38, v148
	v_mov_b32_e32 v39, v149
	v_mov_b32_e32 v40, v150
	v_mov_b32_e32 v41, v151
	s_nop 0
	v_mov_b32_e32 v42, v152
	v_mov_b32_e32 v43, v153
	v_mov_b32_e32 v44, v154
	v_mov_b32_e32 v45, v155
	v_mul_f32_e32 v77, 0x4b800000, v62
	v_cmp_gt_f32_e32 vcc, s21, v62
	v_lshlrev_b32_e32 v63, 16, v64
	v_and_b32_e32 v64, 0xffff0000, v64
	v_cndmask_b32_e32 v62, v62, v77, vcc
	v_rsq_f32_e32 v62, v62
	v_lshlrev_b32_e32 v68, 16, v65
	v_and_b32_e32 v65, 0xffff0000, v65
	v_lshlrev_b32_e32 v72, 16, v59
	v_mul_f32_e32 v77, 0x45800000, v62
	v_cndmask_b32_e32 v62, v62, v77, vcc
	v_mul_f32_e32 v54, v54, v62
	v_mul_f32_e32 v50, v50, v62
	v_mul_f32_e32 v55, v55, v62
	v_mul_f32_e32 v51, v51, v62
	v_and_b32_e32 v59, 0xffff0000, v59
	s_waitcnt vmcnt(4)
	v_lshlrev_b32_e32 v47, 16, v49
	v_lshlrev_b32_e32 v46, 16, v48
	v_and_b32_e32 v49, 0xffff0000, v49
	v_and_b32_e32 v48, 0xffff0000, v48
	v_pk_add_f32 v[56:57], v[46:47], v[48:49]
	s_waitcnt vmcnt(3)
	v_lshlrev_b32_e32 v76, 16, v60
	v_and_b32_e32 v60, 0xffff0000, v60
	v_lshlrev_b32_e32 v62, 16, v61
	v_and_b32_e32 v61, 0xffff0000, v61
	s_waitcnt vmcnt(1)
	v_fma_f32 v38, v38, v54, v42
	v_fma_f32 v39, v39, v50, v43
	v_fma_f32 v40, v40, v55, v44
	v_fmac_f32_e32 v45, v41, v51
	v_fmac_f32_e32 v38, v73, v63
	v_fmac_f32_e32 v39, v73, v64
	v_fmac_f32_e32 v40, v73, v68
	v_fmac_f32_e32 v45, v73, v65
	v_mul_f32_e32 v38, v38, v71
	v_mul_f32_e32 v39, v39, v58
	v_mul_f32_e32 v40, v40, v72
	v_mul_f32_e32 v41, v45, v59
	v_cvt_pk_bf16_f32 v38, v38, v39
	v_cvt_pk_bf16_f32 v39, v40, v41
	global_store_dwordx2 v[30:31], v[38:39], off offset:-512
	s_nop 1
	v_mov_b32_e32 v38, v156
	v_mov_b32_e32 v39, v157
	v_mov_b32_e32 v40, v158
	v_mov_b32_e32 v41, v159
	s_nop 0
	v_mov_b32_e32 v42, v160
	v_mov_b32_e32 v43, v161
	v_mov_b32_e32 v44, v162
	v_mov_b32_e32 v45, v163
	v_add_f32_e32 v54, v56, v57
	v_lshlrev_b32_e32 v51, 16, v53
	v_lshlrev_b32_e32 v50, 16, v52
	v_and_b32_e32 v53, 0xffff0000, v53
	v_and_b32_e32 v52, 0xffff0000, v52
	v_add_f32_dpp v56, v54, v54 quad_perm:[1,0,3,2] row_mask:0xf bank_mask:0xf bound_ctrl:1
	v_pk_add_f32 v[54:55], v[50:51], v[52:53]
	s_nop 0
	v_add_f32_dpp v56, v56, v56 quad_perm:[2,3,0,1] row_mask:0xf bank_mask:0xf bound_ctrl:1
	v_add_f32_e32 v54, v54, v55
	s_nop 0
	v_add_f32_dpp v55, v56, v56 row_half_mirror row_mask:0xf bank_mask:0xf bound_ctrl:1
	v_add_f32_dpp v54, v54, v54 quad_perm:[1,0,3,2] row_mask:0xf bank_mask:0xf bound_ctrl:1
	s_nop 0
	v_add_f32_dpp v55, v55, v55 row_mirror row_mask:0xf bank_mask:0xf bound_ctrl:1
	v_add_f32_dpp v56, v54, v54 quad_perm:[2,3,0,1] row_mask:0xf bank_mask:0xf bound_ctrl:1
	v_mul_f32_e32 v54, 0x3c800000, v55
	s_nop 0
	v_add_f32_dpp v55, v56, v56 row_half_mirror row_mask:0xf bank_mask:0xf bound_ctrl:1
	v_pk_add_f32 v[48:49], v[48:49], v[54:55] op_sel_hi:[1,0] neg_lo:[0,1] neg_hi:[0,1]
	v_pk_add_f32 v[46:47], v[46:47], v[54:55] op_sel_hi:[1,0] neg_lo:[0,1] neg_hi:[0,1]
	v_add_f32_dpp v56, v55, v55 row_mirror row_mask:0xf bank_mask:0xf bound_ctrl:1
	v_mul_f32_e32 v56, 0x3c800000, v56
	v_pk_add_f32 v[52:53], v[52:53], v[56:57] op_sel_hi:[1,0] neg_lo:[0,1] neg_hi:[0,1]
	v_pk_mul_f32 v[54:55], v[48:49], v[48:49]
	v_pk_add_f32 v[50:51], v[50:51], v[56:57] op_sel_hi:[1,0] neg_lo:[0,1] neg_hi:[0,1]
	v_pk_mul_f32 v[56:57], v[52:53], v[52:53]
	v_pk_fma_f32 v[54:55], v[46:47], v[46:47], v[54:55]
	v_pk_fma_f32 v[56:57], v[50:51], v[50:51], v[56:57]
	v_mov_b32_e32 v59, v54
	v_mov_b32_e32 v58, v56
	v_mov_b32_e32 v54, v57
	v_pk_add_f32 v[54:55], v[58:59], v[54:55]
	s_nop 1
	v_mov_b32_dpp v57, v55 quad_perm:[1,0,3,2] row_mask:0xf bank_mask:0xf bound_ctrl:1
	v_mov_b32_dpp v56, v54 quad_perm:[1,0,3,2] row_mask:0xf bank_mask:0xf bound_ctrl:1
	v_pk_add_f32 v[54:55], v[54:55], v[56:57]
	s_nop 1
	v_mov_b32_dpp v57, v55 quad_perm:[2,3,0,1] row_mask:0xf bank_mask:0xf bound_ctrl:1
	v_mov_b32_dpp v56, v54 quad_perm:[2,3,0,1] row_mask:0xf bank_mask:0xf bound_ctrl:1
	v_pk_add_f32 v[54:55], v[54:55], v[56:57]
	s_nop 1
	v_mov_b32_dpp v57, v55 row_half_mirror row_mask:0xf bank_mask:0xf bound_ctrl:1
	v_mov_b32_dpp v56, v54 row_half_mirror row_mask:0xf bank_mask:0xf bound_ctrl:1
	v_pk_add_f32 v[54:55], v[54:55], v[56:57]
	s_nop 1
	v_mov_b32_dpp v57, v55 row_mirror row_mask:0xf bank_mask:0xf bound_ctrl:1
	v_mov_b32_dpp v56, v54 row_mirror row_mask:0xf bank_mask:0xf bound_ctrl:1
	v_pk_add_f32 v[54:55], v[54:55], v[56:57]
	s_nop 0
	v_pk_fma_f32 v[54:55], v[54:55], s[20:21], v[36:37] op_sel_hi:[1,0,0]
	s_nop 0
	v_mul_f32_e32 v36, 0x4b800000, v55
	v_cmp_gt_f32_e32 vcc, s21, v55
	s_nop 1
	v_cndmask_b32_e32 v36, v55, v36, vcc
	v_rsq_f32_e32 v36, v36
	s_nop 0
	v_mul_f32_e32 v37, 0x45800000, v36
	v_cndmask_b32_e32 v36, v36, v37, vcc
	v_mul_f32_e32 v37, v46, v36
	v_mul_f32_e32 v46, v48, v36
	v_mul_f32_e32 v47, v47, v36
	v_mul_f32_e32 v36, v49, v36
	v_cmp_lt_i32_e32 vcc, s23, v1
	s_or_b64 s[18:19], vcc, s[18:19]
	v_mul_f32_e32 v48, 0x4b800000, v54
	v_cmp_gt_f32_e32 vcc, s21, v54
	v_fma_f32 v37, v38, v37, v42
	v_fma_f32 v38, v39, v46, v43
	v_fma_f32 v39, v40, v47, v44
	v_fmac_f32_e32 v45, v41, v36
	v_fmac_f32_e32 v37, v74, v69
	v_fmac_f32_e32 v38, v74, v66
	v_fmac_f32_e32 v39, v74, v70
	v_fmac_f32_e32 v45, v74, v67
	v_mul_f32_e32 v36, v37, v76
	v_mul_f32_e32 v37, v38, v60
	v_mul_f32_e32 v38, v39, v62
	v_mul_f32_e32 v39, v45, v61
	v_cvt_pk_bf16_f32 v36, v36, v37
	v_cvt_pk_bf16_f32 v37, v38, v39
	global_store_dwordx2 v[30:31], v[36:37], off
	s_nop 1
	v_mov_b32_e32 v36, v164
	v_mov_b32_e32 v37, v165
	v_mov_b32_e32 v38, v166
	v_mov_b32_e32 v39, v167
	s_nop 0
	v_mov_b32_e32 v40, v168
	v_mov_b32_e32 v41, v169
	v_mov_b32_e32 v42, v170
	v_mov_b32_e32 v43, v171
	v_cndmask_b32_e32 v48, v54, v48, vcc
	v_rsq_f32_e32 v48, v48
	v_lshlrev_b32_e32 v44, 16, v32
	v_and_b32_e32 v32, 0xffff0000, v32
	v_lshlrev_b32_e32 v45, 16, v33
	v_mul_f32_e32 v49, 0x45800000, v48
	v_cndmask_b32_e32 v48, v48, v49, vcc
	v_mul_f32_e32 v49, v50, v48
	v_mul_f32_e32 v50, v52, v48
	v_mul_f32_e32 v51, v51, v48
	v_mul_f32_e32 v48, v53, v48
	v_and_b32_e32 v33, 0xffff0000, v33
	v_lshlrev_b32_e32 v46, 16, v34
	v_and_b32_e32 v34, 0xffff0000, v34
	v_lshlrev_b32_e32 v47, 16, v35
	v_and_b32_e32 v35, 0xffff0000, v35
	v_fma_f32 v36, v36, v49, v40
	v_fma_f32 v37, v37, v50, v41
	v_fma_f32 v38, v38, v51, v42
	v_fmac_f32_e32 v43, v39, v48
	v_fmac_f32_e32 v36, v75, v44
	v_fmac_f32_e32 v37, v75, v32
	v_fmac_f32_e32 v38, v75, v45
	v_fmac_f32_e32 v43, v75, v33
	v_mul_f32_e32 v32, v36, v46
	v_mul_f32_e32 v33, v37, v34
	v_mul_f32_e32 v34, v38, v47
	v_mul_f32_e32 v35, v43, v35
	v_cvt_pk_bf16_f32 v32, v32, v33
	v_cvt_pk_bf16_f32 v33, v34, v35
	global_store_dwordx2 v[30:31], v[32:33], off offset:512
	s_andn2_b64 exec, exec, s[18:19]
	s_cbranch_execnz .LBB0_628
